# T2: GEMM1 tail ticket queue: fetch_add issued one step ahead (first while the last unit's stores drain, next at quadrant start), parked in v255 lane 20
# baseline (speedup 1.0000x reference)
; #define LAS __attribute__((address_space(3)))
;     __device__ bool next(int i, Unit& u) const { const long L = (long)i * G + c; if (L >= hi) return false; unit_of((int)L, u); return true; }
;     __device__ __forceinline__ void prepare(LAS unsigned char* lds, const pg8::StaticOrder& S, int tid) const {
;         const float* SS = (const float*)(ws + WS_SS);
;         f32x4 p0[9], p1[9];
; #pragma unroll
;         for (int i = 0; i < 9; ++i) {
;             pg8::Unit u; p0[i] = (f32x4){0.f, 0.f, 0.f, 0.f}; p1[i] = p0[i];
;             if (S.next(i, u)) { const float* sp = SS + (size_t)(u.pm * 256 + (tid >> 1)) * 16 + (tid & 1) * 8; p0[i] = *(const f32x4*)sp; p1[i] = *(const f32x4*)(sp + 4); }
; __global__ void __launch_bounds__(NTHREADS, 2) hymba_fwd(Args a) {
;     ...
;             pg8::Gemm g{(const f16*)(a.ws + WS_XH), (const f16*)(a.ws + WS_W1T) + (size_t)layer * N1 * 1024, MROWS, N1, 1024, nullptr};
;             pg8::StaticOrder S; S.init(MROWS, N1, gridDim.x, blockIdx.x);
;             const bool split = (gridDim.x == 256);
;             if (split) S.hi = 2048;
;             Epi1 E{a.ws, a.qgain + layer * 64, a.kgain + layer * 64};
;             pg8::gemm_phase<Epi1, false>(lds, g, S, E);
.LBB0_166:
	s_andn2_b64 vcc, exec, s[0:1]
	s_cbranch_vccnz .LBB0_384
	v_readlane_b32 s0, v254, 51
	s_load_dword s94, s[86:87], 0x0
	v_readlane_b32 s1, v254, 52
	s_mov_b32 s5, s1
	s_mul_i32 s4, s99, 0x2c0000
	s_lshl_b64 s[0:1], s[4:5], 1
	v_readlane_b32 s4, v254, 2
	s_add_u32 s96, s4, s0
	v_readlane_b32 s0, v254, 3
	s_addc_u32 s97, s0, s1
	s_waitcnt lgkmcnt(0)
	s_cmpk_eq_i32 s94, 0x100
	s_cselect_b64 s[6:7], -1, 0
	s_and_b64 s[0:1], s[6:7], exec
	s_movk_i32 s0, 0x800
	s_cselect_b32 s98, s0, 0x840
	s_mov_b32 s101, 0
	s_lshl_b32 s4, s99, 6
	v_writelane_b32 v254, s4, 51
	v_mov_b32_e32 v76, v0
	s_cmp_ge_i32 s2, s98
	v_writelane_b32 v254, s5, 52
	v_readfirstlane_b32 s10, v76
	s_cbranch_scc1 .LBB0_317
	s_waitcnt vmcnt(0)
	v_lshlrev_b32_e32 v2, 5, v76
	v_readlane_b32 s0, v254, 4
	v_and_b32_e32 v194, 32, v2
	v_readlane_b32 s1, v254, 5
	v_ashrrev_i32_e32 v77, 1, v76
	v_writelane_b32 v255, s6, 2
	v_lshl_add_u64 v[74:75], s[0:1], 0, v[194:195]
	v_readlane_b32 s0, v254, 29
	v_writelane_b32 v255, s7, 3
	s_ashr_i32 s4, s94, 31
	v_add_u32_e32 v2, s0, v77
	v_ashrrev_i32_e32 v3, 31, v2
	v_lshlrev_b64 v[2:3], 6, v[2:3]
	v_lshl_add_u64 v[2:3], v[74:75], 0, v[2:3]
	global_load_dwordx4 v[6:9], v[2:3], off offset:16
	global_load_dwordx4 v[10:13], v[2:3], off
	v_readlane_b32 s0, v254, 51
	v_readlane_b32 s1, v254, 52
	v_writelane_b32 v255, s99, 4
	s_mov_b32 s99, s1
	s_add_u32 s0, s94, s2
	s_addc_u32 s1, s4, s3
	v_mov_b64_e32 v[2:3], s[98:99]
	v_cmp_ge_i64_e32 vcc, s[0:1], v[2:3]
	v_mov_b32_e32 v2, 0
	s_and_b64 vcc, exec, vcc
	v_mov_b32_e32 v14, 0
	v_mov_b32_e32 v15, 0
	v_mov_b32_e32 v16, 0
	v_mov_b32_e32 v17, 0
	v_mov_b32_e32 v18, 0
	v_mov_b32_e32 v19, 0
	v_mov_b32_e32 v20, 0
	v_mov_b32_e32 v21, 0
	s_cbranch_vccnz .LBB0_170
	s_ashr_i32 s5, s0, 31
	s_lshr_b32 s5, s5, 29
	s_add_i32 s5, s0, s5
	s_ashr_i32 s6, s5, 3
	s_and_b32 s5, s5, -8
	s_sub_i32 s5, s0, s5
	s_cmp_lt_i32 s5, 0
	s_movk_i32 s7, 0x109
	s_cselect_b32 s7, s7, 0x108
	s_mul_i32 s5, s5, s7
	s_add_i32 s5, s5, s6
	s_mul_hi_i32 s6, s5, 0x2e8ba2e9
	s_lshr_b32 s7, s6, 31
	s_ashr_i32 s6, s6, 3
	s_add_i32 s6, s6, s7
	s_lshl_b32 s7, s6, 2
	s_sub_i32 s8, 0xc0, s7
	s_min_i32 s8, s8, 4
	s_abs_i32 s8, s8
	v_cvt_f32_u32_e32 v3, s8
	s_sub_i32 s9, 0, s8
	s_mul_i32 s6, s6, 44
	s_sub_i32 s5, s5, s6
	v_rcp_iflag_f32_e32 v3, v3
	s_ashr_i32 s6, s5, 31
	s_abs_i32 s5, s5
	v_mul_f32_e32 v3, 0x4f7ffffe, v3
	v_cvt_u32_f32_e32 v3, v3
	s_nop 0
	v_readfirstlane_b32 s11, v3
	s_mul_i32 s9, s9, s11
	s_mul_hi_u32 s9, s11, s9
	s_add_i32 s11, s11, s9
	s_mul_hi_u32 s9, s5, s11
	s_mul_i32 s9, s9, s8
	s_sub_i32 s5, s5, s9
	s_sub_i32 s9, s5, s8
	s_cmp_ge_u32 s5, s8
	s_cselect_b32 s5, s9, s5
	s_sub_i32 s9, s5, s8
	s_cmp_ge_u32 s5, s8
	s_cselect_b32 s5, s9, s5
	s_xor_b32 s5, s5, s6
	s_sub_i32 s5, s5, s6
	s_add_i32 s7, s7, s5
	v_lshl_add_u32 v4, s7, 8, v77
	v_ashrrev_i32_e32 v5, 31, v4
	v_lshlrev_b64 v[4:5], 6, v[4:5]
	v_lshl_add_u64 v[4:5], v[74:75], 0, v[4:5]
	global_load_dwordx4 v[14:17], v[4:5], off
	global_load_dwordx4 v[18:21], v[4:5], off offset:16

; #define LAS __attribute__((address_space(3)))
; __global__ void __launch_bounds__(NTHREADS, 2) hymba_fwd(Args a) {
;     ...
;             if (split) {
;                 unsigned* tailq = (unsigned*)(a.ws + WS_BAR) + 3584 + 64 * layer;
;                 volatile LAS unsigned* qslot = (volatile LAS unsigned*)(lds + LDS_MISC) + 8;
;                 for (;;) {
;                     if (threadIdx.x == 0) *qslot = __hip_atomic_fetch_add(tailq, 1u, __ATOMIC_RELAXED, __HIP_MEMORY_SCOPE_AGENT);
.LBB0_316:
	v_readlane_b32 s6, v255, 2
	v_readlane_b32 s7, v255, 3
	v_readlane_b32 s82, v254, 55
	v_readlane_b32 s83, v254, 56
	s_nop 3
	s_cmp_eq_u64 s[6:7], 0
	s_cbranch_scc1 .Lt2_a
	v_readlane_b32 s0, v254, 51
	v_readlane_b32 s1, v254, 52
	s_lshl_b64 s[0:1], s[0:1], 2
	v_readlane_b32 s4, v254, 16
	s_add_u32 s0, s4, s0
	v_readlane_b32 s4, v254, 17
	s_addc_u32 s1, s4, s1
	s_mov_b64 s[10:11], exec
	s_lshl_b64 s[12:13], s[82:83], 20
	v_mov_b32_e32 v71, 1
	v_mov_b32_e32 v72, 0
	s_mov_b64 exec, s[12:13]
	global_atomic_add v255, v72, v71, s[0:1] sc0
	s_mov_b64 exec, s[10:11]
	s_mov_b32 s101, 1

; #define LAS __attribute__((address_space(3)))
; __device__ __forceinline__ void gemm1_tail_quadrant(LAS unsigned char* lds, const f16* A, const f16* Bt, unsigned char* ws, int pm, int pn, int ai, int bj) {
;     ...
;     const float* SS = (const float*)(ws + WS_SS); f16* Z = (f16*)(ws + WS_Z);
;     const int row0 = pm * 256 + ai * 128 + wr * 64 + fr;
;     f32x4 part[4];
; #pragma unroll
;     for (int m = 0; m < 4; ++m) part[m] = *(const f32x4*)(SS + (size_t)(row0 + m * 16) * 16 + 4 * fq);
; #pragma unroll
;     for (int m = 0; m < 4; ++m) {
;         float t = (part[m][0] + part[m][1]) + (part[m][2] + part[m][3]);
;         t = sum_fq(t);
;         const float rs = __builtin_amdgcn_rsqf(t * (1.0f / 1024.0f) + EPS);
;         const int row = row0 + m * 16;
;         float v[8];
; #pragma unroll
;         for (int e = 0; e < 8; ++e) v[e] = acc[m][e >> 2][e & 3] * rs;
;         const int cg8 = 8 * (wc & 1) + 4 * bj + fq;
;         f16* p = Z + (((size_t)(((row >> 12) * 4 + (pn - 7)) * 16 + cg8) * 4096 + (row & 4095)) * 2 + (wc >> 1)) * 8;
;         *(u32x4*)p = pack8(v);
;     }
;     asm volatile("s_waitcnt vmcnt(0)" ::: "memory");
;     __syncthreads();
; __global__ void __launch_bounds__(NTHREADS, 2) hymba_fwd(Args a) {
;     ...
;             if (split) {
;                 unsigned* tailq = (unsigned*)(a.ws + WS_BAR) + 3584 + 64 * layer;
;                 volatile LAS unsigned* qslot = (volatile LAS unsigned*)(lds + LDS_MISC) + 8;
;                 for (;;) {
;                     if (threadIdx.x == 0) *qslot = __hip_atomic_fetch_add(tailq, 1u, __ATOMIC_RELAXED, __HIP_MEMORY_SCOPE_AGENT);
;                     __syncthreads();
;                     const unsigned q = *qslot;
;                     __syncthreads();
;                     if (q >= 256u) break;
;                     pg8::Unit tu; S.unit_of(2048 + (int)(q >> 2), tu);
;                     gemm1_tail_quadrant(lds, g.A, g.Bt, a.ws, tu.pm, tu.pn, (int)((q >> 1) & 1u), (int)(q & 1u));
.LBB0_317:
	v_readlane_b32 s94, v255, 0
	s_andn2_b64 vcc, exec, s[6:7]
	v_readlane_b32 s53, v254, 41
	v_readlane_b32 s64, v254, 42
	v_readlane_b32 s95, v255, 1
	s_cbranch_vccnz .LBB0_338
	v_readlane_b32 s0, v254, 51
	v_readlane_b32 s1, v254, 52
	s_lshl_b64 s[0:1], s[0:1], 2
	v_readlane_b32 s4, v254, 16
	s_add_u32 s0, s4, s0
	v_readlane_b32 s4, v254, 17
	s_addc_u32 s1, s4, s1
	s_mul_i32 s5, s99, 0x580000
	v_readlane_b32 s6, v254, 43
	s_mul_hi_u32 s4, s99, 0x580000
	s_add_u32 s8, s6, s5
	v_readlane_b32 s5, v254, 44
	s_addc_u32 s9, s5, s4
	s_cmp_lg_u32 s101, 0
	s_cbranch_scc1 .Lt2_b
	s_mov_b64 s[10:11], exec
	s_lshl_b64 s[12:13], s[82:83], 20
	v_mov_b32_e32 v71, 1
	v_mov_b32_e32 v72, 0
	s_mov_b64 exec, s[12:13]
	global_atomic_add v255, v72, v71, s[0:1] sc0
	s_mov_b64 exec, s[10:11]
	s_mov_b32 s101, 1
.Lt2_b:
	s_branch .LBB0_321
.LBB0_319:
	s_and_b32 s4, 0xffff, s14
	s_lshl_b32 s6, s13, 7
	s_lshl_b32 s4, s4, 8
	s_or_b32 s4, s4, s6
	s_add_i32 s4, s4, s31
	v_or_b32_e32 v54, s4, v23
	v_readlane_b32 s6, v254, 4
	v_mov_b32_e32 v23, v195
	v_readlane_b32 s7, v254, 5
	v_ashrrev_i32_e32 v55, 31, v54
	v_lshlrev_b64 v[24:25], 6, v[54:55]
	v_lshl_add_u64 v[22:23], s[6:7], 0, v[22:23]
	v_lshl_add_u64 v[24:25], v[22:23], 0, v[24:25]
	global_load_dwordx4 v[46:49], v[24:25], off
	v_or_b32_e32 v24, 16, v54
	v_ashrrev_i32_e32 v25, 31, v24
	v_lshlrev_b64 v[24:25], 6, v[24:25]
	v_lshl_add_u64 v[24:25], v[22:23], 0, v[24:25]
	global_load_dwordx4 v[50:53], v[24:25], off
	v_or_b32_e32 v24, 32, v54
	v_ashrrev_i32_e32 v25, 31, v24
	v_lshlrev_b64 v[24:25], 6, v[24:25]
	v_lshl_add_u64 v[24:25], v[22:23], 0, v[24:25]
	global_load_dwordx4 v[30:33], v[24:25], off
	v_or_b32_e32 v24, 48, v54
	v_ashrrev_i32_e32 v25, 31, v24
	v_lshlrev_b64 v[24:25], 6, v[24:25]
	v_lshl_add_u64 v[22:23], v[22:23], 0, v[24:25]
	global_load_dwordx4 v[22:25], v[22:23], off
	s_ashr_i32 s4, s4, 10
	s_and_b32 s5, 0xffff, s15
	s_lshl_b32 s6, s12, 3
	s_and_b32 s4, s4, 0xffffffc
	s_and_b32 s6, s6, 8
	s_lshl_b32 s7, s11, 2
	s_add_i32 s5, s5, s4
	s_or_b32 s6, s6, s7
	s_lshl_b32 s4, s5, 4
	s_or_b32 s4, s4, s6
	s_addk_i32 s4, 0xff90
	v_or_b32_e32 v42, s4, v44
	v_mov_b32_e32 v44, v54
	v_and_b32_e32 v45, 0xfcf, v44
	v_ashrrev_i32_e32 v43, 31, v42
	v_lshlrev_b64 v[42:43], 13, v[42:43]
	s_lshr_b32 s4, s10, 1
	s_lshl_b32 s4, s4, 12
	v_or3_b32 v42, v42, s4, v45
	s_mov_b64 s[4:5], 0
	s_waitcnt vmcnt(0)
	v_add_f32_e32 v44, v46, v47
	v_add_f32_e32 v46, v48, v49
	v_add_f32_e32 v44, v44, v46
	v_mov_b32_e32 v46, v44
	s_nop 1
	v_permlane16_swap_b32_e32 v44, v46
	v_add_f32_e32 v44, v44, v46
	v_mov_b32_e32 v46, v44
	s_nop 1
	v_permlane32_swap_b32_e32 v44, v46
	v_add_f32_e32 v44, v44, v46
	v_fmamk_f32 v44, v44, 0x3a800000, v1
	v_rsq_f32_e32 v44, v44
	v_lshl_add_u64 v[46:47], v[42:43], 4, s[16:17]
	v_fma_mixlo_f16 v45, v38, v44, 0
	v_mov_b32_e32 v38, v39
	v_mov_b32_e32 v39, v40
	v_pk_mov_b32 v[40:41], v[40:41], v[34:35] op_sel:[1,0]
	v_mov_b32_e32 v34, v35
	v_mov_b32_e32 v35, v36
	v_pk_mul_f32 v[38:39], v[38:39], v[44:45] op_sel_hi:[1,0]
	v_pk_mul_f32 v[40:41], v[40:41], v[44:45] op_sel_hi:[1,0]
	v_pk_mul_f32 v[34:35], v[34:35], v[44:45] op_sel_hi:[1,0]
	v_cvt_pk_f16_f32 v39, v38, v39
	v_cvt_pk_f16_f32 v40, v40, v41
	v_cvt_pk_f16_f32 v34, v34, v35
	v_pack_b32_f16 v38, v45, v39
	v_alignbit_b32 v39, v40, v39, 16
	v_alignbit_b32 v40, v34, v40, 16
	v_lshrrev_b32_e32 v41, 16, v34
	v_add_f32_e32 v34, v50, v51
	v_add_f32_e32 v35, v52, v53
	v_add_f32_e32 v34, v34, v35
	v_mov_b32_e32 v35, v34
	s_nop 1
	v_permlane16_swap_b32_e32 v34, v35
	v_add_f32_e32 v34, v34, v35
	v_mov_b32_e32 v35, v34
	s_nop 1
	v_permlane32_swap_b32_e32 v34, v35
	v_add_f32_e32 v34, v34, v35
	v_fmamk_f32 v34, v34, 0x3a800000, v1
	v_rsq_f32_e32 v36, v34
	v_fma_mixhi_f16 v41, v37, v44, 0
	v_or_b32_e32 v34, 16, v42
	v_mov_b32_e32 v35, v43
	v_fma_mixlo_f16 v37, v26, v36, 0
	v_mov_b32_e32 v26, v27
	v_mov_b32_e32 v27, v28
	v_pk_mov_b32 v[28:29], v[28:29], v[18:19] op_sel:[1,0]
	v_mov_b32_e32 v18, v19
	v_mov_b32_e32 v19, v20
	v_pk_mul_f32 v[26:27], v[26:27], v[36:37] op_sel_hi:[1,0]
	v_pk_mul_f32 v[28:29], v[28:29], v[36:37] op_sel_hi:[1,0]
	v_pk_mul_f32 v[18:19], v[18:19], v[36:37] op_sel_hi:[1,0]
	v_cvt_pk_f16_f32 v27, v26, v27
	v_cvt_pk_f16_f32 v28, v28, v29
	v_cvt_pk_f16_f32 v18, v18, v19
	v_pack_b32_f16 v26, v37, v27
	v_alignbit_b32 v27, v28, v27, 16
	v_alignbit_b32 v28, v18, v28, 16
	v_lshrrev_b32_e32 v29, 16, v18
	v_add_f32_e32 v18, v30, v31
	v_add_f32_e32 v19, v32, v33
	v_add_f32_e32 v18, v18, v19
	v_mov_b32_e32 v19, v18
	s_nop 1
	v_permlane16_swap_b32_e32 v18, v19
	v_add_f32_e32 v18, v18, v19
	v_mov_b32_e32 v19, v18
	s_nop 1
	v_permlane32_swap_b32_e32 v18, v19
	v_add_f32_e32 v18, v18, v19
	v_fmamk_f32 v18, v18, 0x3a800000, v1
	v_rsq_f32_e32 v18, v18
	v_fma_mixhi_f16 v29, v21, v36, 0
	v_or_b32_e32 v20, 32, v42
	v_mov_b32_e32 v21, v43
	v_fma_mixlo_f16 v19, v14, v18, 0
	v_mov_b32_e32 v14, v15
	v_mov_b32_e32 v15, v16
	v_pk_mov_b32 v[16:17], v[16:17], v[10:11] op_sel:[1,0]
	v_mov_b32_e32 v10, v11
	v_mov_b32_e32 v11, v12
	v_pk_mul_f32 v[14:15], v[14:15], v[18:19] op_sel_hi:[1,0]
	v_pk_mul_f32 v[16:17], v[16:17], v[18:19] op_sel_hi:[1,0]
	v_pk_mul_f32 v[10:11], v[10:11], v[18:19] op_sel_hi:[1,0]
	v_cvt_pk_f16_f32 v15, v14, v15
	v_cvt_pk_f16_f32 v16, v16, v17
	v_cvt_pk_f16_f32 v10, v10, v11
	v_pack_b32_f16 v14, v19, v15
	v_alignbit_b32 v15, v16, v15, 16
	v_alignbit_b32 v16, v10, v16, 16
	v_lshrrev_b32_e32 v17, 16, v10
	v_add_f32_e32 v10, v22, v23
	v_add_f32_e32 v11, v24, v25
	v_add_f32_e32 v10, v10, v11
	v_mov_b32_e32 v11, v10
	s_nop 1
	v_permlane16_swap_b32_e32 v10, v11
	v_add_f32_e32 v10, v10, v11
	v_mov_b32_e32 v11, v10
	s_nop 1
	v_permlane32_swap_b32_e32 v10, v11
	v_add_f32_e32 v10, v10, v11
	v_fmamk_f32 v10, v10, 0x3a800000, v1
	v_rsq_f32_e32 v10, v10
	v_or_b32_e32 v42, 48, v42
	v_lshl_add_u64 v[34:35], v[34:35], 4, s[16:17]
	v_lshl_add_u64 v[20:21], v[20:21], 4, s[16:17]
	v_fma_mixlo_f16 v11, v2, v10, 0
	v_mov_b32_e32 v2, v3
	v_mov_b32_e32 v3, v4
	v_pk_mov_b32 v[4:5], v[4:5], v[6:7] op_sel:[1,0]
	v_pk_mul_f32 v[2:3], v[2:3], v[10:11] op_sel_hi:[1,0]
	v_pk_mul_f32 v[4:5], v[4:5], v[10:11] op_sel_hi:[1,0]
	v_cvt_pk_f16_f32 v3, v2, v3
	v_cvt_pk_f16_f32 v6, v4, v5
	v_mov_b32_e32 v4, v7
	v_mov_b32_e32 v5, v8
	v_pk_mul_f32 v[4:5], v[4:5], v[10:11] op_sel_hi:[1,0]
	v_fma_mixhi_f16 v17, v13, v18, 0
	v_cvt_pk_f16_f32 v5, v4, v5
	v_alignbit_b32 v4, v5, v6, 16
	v_lshrrev_b32_e32 v5, 16, v5
	v_lshl_add_u64 v[12:13], v[42:43], 4, s[16:17]
	v_pack_b32_f16 v2, v11, v3
	v_alignbit_b32 v3, v6, v3, 16
	v_fma_mixhi_f16 v5, v9, v10, 0
	global_store_dwordx4 v[46:47], v[38:41], off
	global_store_dwordx4 v[34:35], v[26:29], off
	global_store_dwordx4 v[20:21], v[14:17], off
	global_store_dwordx4 v[12:13], v[2:5], off
	s_waitcnt vmcnt(0)
	s_barrier

; __device__ __forceinline__ void gemm1_tail_quadrant(LAS unsigned char* lds, const f16* A, const f16* Bt, unsigned char* ws, int pm, int pn, int ai, int bj) {
;     ...
;     constexpr int K = 1024, NT = K / BK;
;     unsigned voff[2];
; #pragma unroll
;     for (int i = 0; i < 2; ++i) { int R, C; stage_rc(tid * 16 + i * 8192, R, C); voff[i] = (unsigned)(R * K + C) * 2u; }
;     const char* abase = (const char*)A + ((size_t)pm * 256 + ai * 128) * K * 2;
;     const char* bbase = (const char*)Bt + ((size_t)pn * 256 + bj * 128) * K * 2;
;     const unsigned ldsw = (unsigned)wid * 1024u;
;     const int aoff = lds_byte(wr * 64 + fr, fq * 8), boff = lds_byte(wc * 32 + fr, fq * 8);
;     ...
;     f32x4 acc[4][2];
; #pragma unroll
;     for (int m = 0; m < 4; ++m)
; #pragma unroll
;         for (int n = 0; n < 2; ++n) acc[m][n] = (f32x4){0.f, 0.f, 0.f, 0.f};
;     QSTAGE(0, 0); QSTAGE(1, 1); QSTAGE(2, 2);
; __global__ void __launch_bounds__(NTHREADS, 2) hymba_fwd(Args a) {
;     ...
;                 for (;;) {
;                     if (threadIdx.x == 0) *qslot = __hip_atomic_fetch_add(tailq, 1u, __ATOMIC_RELAXED, __HIP_MEMORY_SCOPE_AGENT);
;                     __syncthreads();
;                     const unsigned q = *qslot;
;                     __syncthreads();
;                     if (q >= 256u) break;
;                     pg8::Unit tu; S.unit_of(2048 + (int)(q >> 2), tu);
;                     gemm1_tail_quadrant(lds, g.A, g.Bt, a.ws, tu.pm, tu.pn, (int)((q >> 1) & 1u), (int)(q & 1u));
.LBB0_321:
	s_and_saveexec_b64 s[4:5], s[82:83]
	s_cbranch_execz .LBB0_325
	s_waitcnt vmcnt(0)
	v_readlane_b32 s6, v255, 20
	v_mov_b32_e32 v2, 0
	s_nop 1
	v_add_u32_e32 v2, s6, v2
	v_readlane_b32 s6, v254, 47
	s_nop 1
	v_mov_b32_e32 v3, s6
	ds_write_b32 v3, v2
.LBB0_325:
	s_or_b64 exec, exec, s[4:5]
	v_readlane_b32 s4, v254, 47
	s_waitcnt vmcnt(0) lgkmcnt(0)
	s_barrier
	v_mov_b32_e32 v2, s4
	ds_read_b32 v2, v2
	s_movk_i32 s4, 0xff
	s_waitcnt lgkmcnt(0)
	s_barrier
	v_cmp_lt_u32_e32 vcc, s4, v2
	v_readfirstlane_b32 s6, v2
	s_mov_b64 s[4:5], -1
	s_cbranch_vccnz .LBB0_320
	s_mov_b64 s[10:11], exec
	s_lshl_b64 s[12:13], s[82:83], 20
	v_mov_b32_e32 v71, 1
	v_mov_b32_e32 v72, 0
	s_mov_b64 exec, s[12:13]
	global_atomic_add v255, v72, v71, s[0:1] sc0
	s_mov_b64 exec, s[10:11]
	v_mov_b32_e32 v12, v0
	s_bfe_u32 s4, s6, 0x30002
	v_ashrrev_i32_e32 v3, 31, v12
	v_lshrrev_b32_e32 v3, 26, v3
	v_add_u32_e32 v13, v12, v3
	v_bfe_i32 v3, v12, 27, 1
	v_lshlrev_b32_e32 v2, 4, v12
	v_lshrrev_b32_e32 v3, 22, v3
	v_add_u32_e32 v3, v2, v3
	v_and_b32_e32 v3, 0xfffffc00, v3
	v_sub_u32_e32 v3, v2, v3
	v_lshrrev_b32_e32 v4, 4, v3
	v_bitop3_b32 v3, v4, v3, 32 bitop3:0x6c
	v_ashrrev_i32_e32 v5, 31, v3
	s_mulk_i32 s4, 0x108
	s_lshr_b32 s5, s6, 5
	v_lshrrev_b32_e32 v5, 26, v5
	s_add_i32 s4, s4, s5
	v_add_u32_e32 v5, v3, v5
	s_addk_i32 s4, 0x100
	v_ashrrev_i32_e32 v15, 6, v5
	v_and_b32_e32 v5, 0xc0, v5
	s_and_b32 s5, s4, 0xffff
	v_ashrrev_i32_e32 v14, 6, v13
	v_sub_u32_e32 v3, v3, v5
	s_mul_i32 s5, s5, 0xba2f
	v_lshlrev_b32_e32 v4, 3, v14
	v_lshlrev_b32_e32 v6, 5, v14
	v_ashrrev_i16_sdwa v3, v224, sext(v3) dst_sel:DWORD dst_unused:UNUSED_PAD src0_sel:DWORD src1_sel:BYTE_0
	s_lshr_b32 s5, s5, 21
	v_and_b32_e32 v4, 0x1ffff0, v4
	v_and_b32_e32 v6, 32, v6
	v_bfe_i32 v16, v3, 0, 16
	s_lshl_b32 s7, s5, 2
	s_mul_i32 s5, s5, 44
	v_add_u32_e32 v3, v6, v16
	v_add_lshl_u32 v4, v15, v4, 11
	v_add_u32_e32 v2, 0x2000, v2
	s_sub_i32 s4, s4, s5
	v_lshl_add_u32 v194, v3, 1, v4
	v_ashrrev_i32_e32 v3, 31, v2
	s_and_b32 s5, s4, 3
	s_bfe_u32 s13, s6, 0x10001
	s_and_b32 s11, s6, 1
	v_readfirstlane_b32 s6, v12
	v_lshrrev_b32_e32 v3, 22, v3
	s_or_b32 s14, s5, s7
	s_ashr_i32 s12, s6, 6
	v_add_u32_e32 v3, v2, v3
	s_bfe_u32 s15, s4, 0x60002
	s_and_b32 s10, s12, 3
	v_ashrrev_i32_e32 v17, 10, v3
	s_lshl_b32 s36, s14, 19
	v_mul_i32_i24_e32 v3, 0x400, v17
	s_add_u32 s7, s40, s36
	v_sub_u32_e32 v2, v2, v3
	s_addc_u32 s33, s41, 0
	s_lshl_b32 s37, s11, 18
	s_lshl_b32 s46, s15, 19
	v_lshrrev_b32_e32 v3, 4, v2
	s_add_u32 s4, s96, s46
	v_bitop3_b32 v2, v3, v2, 32 bitop3:0x6c
	s_addc_u32 s5, s97, 0
	v_ashrrev_i32_e32 v4, 31, v2
	s_add_u32 s4, s4, s37
	v_lshrrev_b32_e32 v4, 26, v4
	s_addc_u32 s5, s5, 0
	s_ashr_i32 s31, s6, 2
	v_add_u32_e32 v4, v2, v4
	s_andn2_b32 s31, s31, 63
	s_lshl_b32 s52, s13, 18
	v_ashrrev_i32_e32 v18, 6, v4
	v_and_b32_e32 v4, 0xc0, v4
	s_add_u32 s6, s7, s52
	v_sub_u32_e32 v2, v2, v4
	s_addc_u32 s7, s33, 0
	s_lshl_b32 s33, s12, 10
	v_lshlrev_b32_e32 v3, 3, v17
	v_lshlrev_b32_e32 v5, 5, v17
	v_ashrrev_i16_sdwa v2, v224, sext(v2) dst_sel:DWORD dst_unused:UNUSED_PAD src0_sel:DWORD src1_sel:BYTE_0
	s_add_i32 s33, s33, 0
	v_and_b32_e32 v3, 0x1ffff0, v3
	v_and_b32_e32 v5, 32, v5
	v_bfe_i32 v19, v2, 0, 16
	s_add_i32 s34, s33, 0x4000
	s_mov_b32 m0, s33
	v_add_u32_e32 v2, v5, v19
	v_add_lshl_u32 v3, v18, v3, 11
	global_load_lds_dwordx4 v194, s[6:7]
	s_mov_b32 m0, s34
	v_lshl_add_u32 v2, v2, 1, v3
	global_load_lds_dwordx4 v194, s[4:5]
	s_add_i32 m0, s33, 0x2000
	v_lshl_add_u64 v[4:5], s[6:7], 0, v[194:195]
	v_mov_b32_e32 v3, v195
	global_load_lds_dwordx4 v2, s[6:7]
	s_add_i32 m0, s33, 0x6000
	v_lshl_add_u64 v[6:7], s[4:5], 0, v[194:195]
	v_lshl_add_u64 v[8:9], s[6:7], 0, v[2:3]
	v_lshl_add_u64 v[10:11], s[4:5], 0, v[2:3]
	global_load_lds_dwordx4 v2, s[4:5]
	s_add_i32 m0, s33, 0x8000
	s_add_i32 s4, s33, 0xc000
	v_lshl_add_u64 v[2:3], v[4:5], 0, s[88:89]
	global_load_lds_dwordx4 v[2:3], off
	v_lshl_add_u64 v[2:3], v[6:7], 0, s[88:89]
	s_mov_b32 m0, s4
	s_mov_b64 s[6:7], 0x100
	global_load_lds_dwordx4 v[2:3], off
	v_lshl_add_u64 v[2:3], v[8:9], 0, s[88:89]
	s_add_i32 m0, s33, 0xa000
	s_add_i32 s4, s33, 0x14000
	global_load_lds_dwordx4 v[2:3], off
	v_lshl_add_u64 v[2:3], v[10:11], 0, s[88:89]
	s_add_i32 m0, s33, 0xe000
	v_and_b32_e32 v23, 15, v12
	global_load_lds_dwordx4 v[2:3], off
	s_add_i32 m0, s33, 0x10000
	v_lshl_add_u64 v[2:3], v[4:5], 0, s[6:7]
	global_load_lds_dwordx4 v[2:3], off
	v_lshl_add_u64 v[2:3], v[6:7], 0, s[6:7]
	s_mov_b32 m0, s4
	v_bfe_u32 v44, v12, 4, 2
	global_load_lds_dwordx4 v[2:3], off
	v_lshl_add_u64 v[2:3], v[8:9], 0, s[6:7]
	s_add_i32 m0, s33, 0x12000
	v_lshlrev_b32_e32 v22, 4, v44
	global_load_lds_dwordx4 v[2:3], off
	v_lshl_add_u64 v[2:3], v[10:11], 0, s[6:7]
	s_add_i32 m0, s33, 0x16000
	s_lshl_b32 s34, s31, 7
	global_load_lds_dwordx4 v[2:3], off
	v_lshlrev_b32_e32 v3, 2, v12
	v_lshlrev_b32_e32 v2, 6, v23
	v_and_b32_e32 v3, 32, v3
	v_bitop3_b32 v45, v2, v3, v22 bitop3:0x36
	v_lshlrev_b32_e32 v2, 14, v14
	v_and_b32_e32 v2, 0xffff8000, v2
	v_lshl_add_u32 v2, v15, 11, v2
	v_and_or_b32 v2, v13, 64, v2
	v_lshl_add_u32 v194, v16, 1, v2
	v_lshlrev_b32_e32 v2, 14, v17
	v_and_b32_e32 v2, 0xffff8000, v2
	s_lshl_b32 s35, s10, 12
	s_or_b32 s4, s36, s52
	v_lshl_add_u32 v2, v18, 11, v2
	v_lshlrev_b32_e32 v3, 6, v17
	s_add_u32 s4, s53, s4
	v_and_or_b32 v2, v3, 64, v2
	s_addc_u32 s5, s64, 0
	v_lshl_add_u32 v2, v19, 1, v2
	v_mov_b32_e32 v3, v195
	v_lshl_add_u64 v[24:25], s[4:5], 0, v[194:195]
	v_lshl_add_u64 v[30:31], s[4:5], 0, v[2:3]
	s_or_b32 s4, s46, s37
	s_add_u32 s4, s8, s4
	s_addc_u32 s5, s9, 0
	v_mov_b32_e32 v38, 0
	v_lshl_add_u64 v[32:33], s[4:5], 0, v[194:195]
	v_lshl_add_u64 v[42:43], s[4:5], 0, v[2:3]
	s_mov_b32 s36, 0
	s_mov_b32 s37, 0x18000
	s_mov_b64 s[4:5], 0
	v_mov_b32_e32 v39, v38
	v_mov_b32_e32 v40, v38
	v_mov_b32_e32 v41, v38
	v_mov_b32_e32 v34, v38
	v_mov_b32_e32 v35, v38
	v_mov_b32_e32 v36, v38
	v_mov_b32_e32 v37, v38
	v_mov_b32_e32 v26, v38
	v_mov_b32_e32 v27, v38
	v_mov_b32_e32 v28, v38
	v_mov_b32_e32 v29, v38
	v_mov_b32_e32 v18, v38
	v_mov_b32_e32 v19, v38
	v_mov_b32_e32 v20, v38
	v_mov_b32_e32 v21, v38
	v_mov_b32_e32 v14, v38
	v_mov_b32_e32 v15, v38
	v_mov_b32_e32 v16, v38
	v_mov_b32_e32 v17, v38
	v_mov_b32_e32 v10, v38
	v_mov_b32_e32 v11, v38
	v_mov_b32_e32 v12, v38
	v_mov_b32_e32 v13, v38
	v_mov_b32_e32 v2, v38
	v_mov_b32_e32 v3, v38
	v_mov_b32_e32 v4, v38
	v_mov_b32_e32 v5, v38
	v_mov_b32_e32 v6, v38
	v_mov_b32_e32 v7, v38
	v_mov_b32_e32 v8, v38
	v_mov_b32_e32 v9, v38
	s_branch .LBB0_328
